# speedup vs baseline: 1.0649x; 1.0285x over previous
; __device__ __forceinline__ int tid_opaque() { int t = threadIdx.x; asm volatile("" : "+v"(t)); return t; }
; __device__ __forceinline__ void phase_peer_u(const Params& p, int layer, int xs, int wid0, int wstride, char* smraw) {
;   const int tid = tid_opaque(), l = tid & 63, g = l >> 3, j = l & 7;
;   const int wid = wid0 + (tid >> 6);
;   char* xqs = smraw + (tid >> 6) * 256;
;   const int sl = xs >> 1, par = xs & 1;
;   constexpr int TH = T / 2;
;   const unsigned char* Uq = p.Uq + (size_t)(layer * 4 + sl) * NEXP * 128;
;   const unsigned joff = j * 16;
;   u32x4 ni[4];
;   auto load_idx = [&](int tt) {
;     const u32x4* ip = (const u32x4*)((const char*)p.sel_idx + ((unsigned)(2 * tt + par) * 512u + (unsigned)g * 64u));
; #pragma unroll
;     for (int q4 = 0; q4 < 4; ++q4) ni[q4] = ip[q4];
;   };
;   auto issue_rows = [&](int tt, u32x4 (&q)[16], u32x2& xv) {
; #pragma unroll
;     for (int i = 0; i < 16; ++i) q[i] = *(const u32x4*)(Uq + (ni[i >> 2][i & 3] * 128u + joff));
;     xv = *(const u32x2*)((const char*)p.hb + ((unsigned)(2 * tt + par) * 2048u + (unsigned)(sl * 512 + l * 8)));
;   };
;     ...
;   u32x4 qA[16], qB[16]; u32x2 xA = {0u, 0u}, xB = {0u, 0u};
;   int tt = wid;
;   if (tt < TH) { load_idx(tt); issue_rows(tt, qA, xA); if (tt + wstride < TH) load_idx(tt + wstride); }
.LBB0_670:
	s_or_b64 exec, exec, s[0:1]
	v_mov_b32_e32 v16, v189
	s_barrier
	s_ashr_i32 s14, s3, 1
	s_waitcnt vmcnt(5)
	v_ashrrev_i32_e32 v80, 6, v16
	v_add_u32_e32 v169, s92, v80
	s_and_b32 s28, s3, 1
	s_ashr_i32 s15, s14, 31
	s_movk_i32 s3, 0x4020
	s_lshl_b64 s[0:1], s[14:15], 21
	v_cmp_gt_i32_e32 vcc, s3, v169
	s_mul_i32 s29, s33, 3
	s_and_saveexec_b64 s[8:9], vcc
	s_cbranch_execz .LBB0_689
	v_and_b32_e32 v6, 63, v189
	v_lshrrev_b32_e32 v7, 6, v189
	v_lshlrev_b32_e32 v0, 3, v6
	v_and_b32_e32 v1, 7, v6
	v_cmp_eq_u32_e64 s[72:73], 0, v1
	v_lshlrev_b32_e32 v1, 4, v1
	v_lshrrev_b32_e32 v8, 3, v6
	v_readfirstlane_b32 s70, v7
	s_lshl_b32 s71, s28, 9
	v_lshl_add_u32 v2, v8, 6, s71
	v_lshlrev_b32_e32 v5, 6, v8
	v_lshlrev_b32_e32 v3, 8, v7
	v_lshl_add_u32 v4, v1, 1, v3
	v_lshl_add_u32 v3, v6, 2, v3
	s_add_u32 s60, s92, s70
	s_movk_i32 s61, 0x4020
	s_cmp_ge_u32 s60, s61
	s_cbranch_scc1 .Lmy_pu0_done
	s_lshl_b32 s70, s14, 21
	s_add_u32 s66, s88, s70
	s_addc_u32 s67, s89, 0
	v_readlane_b32 s64, v254, 4
	v_readlane_b32 s65, v254, 5
	s_lshl_b32 s68, s14, 9
	s_mov_b32 s69, 0x42fe0000
	s_mov_b32 s21, 0xf0f0f0f
	s_lshl_b32 s70, s60, 10
	v_add_u32_e32 v9, s70, v2
	global_load_dwordx4 v[10:13], v9, s[52:53]
	global_load_dwordx4 v[14:17], v9, s[52:53] offset:16
	global_load_dwordx4 v[18:21], v9, s[52:53] offset:32
	global_load_dwordx4 v[22:25], v9, s[52:53] offset:48
	s_waitcnt vmcnt(0)
	v_lshl_add_u32 v6, v10, 7, v1
	global_load_dwordx4 v[106:109], v6, s[66:67]
	v_lshl_add_u32 v7, v11, 7, v1
	global_load_dwordx4 v[110:113], v7, s[66:67]
	v_lshl_add_u32 v6, v12, 7, v1
	global_load_dwordx4 v[114:117], v6, s[66:67]
	v_lshl_add_u32 v7, v13, 7, v1
	global_load_dwordx4 v[118:121], v7, s[66:67]
	v_lshl_add_u32 v6, v14, 7, v1
	global_load_dwordx4 v[122:125], v6, s[66:67]
	v_lshl_add_u32 v7, v15, 7, v1
	global_load_dwordx4 v[126:129], v7, s[66:67]
	v_lshl_add_u32 v6, v16, 7, v1
	global_load_dwordx4 v[130:133], v6, s[66:67]
	v_lshl_add_u32 v7, v17, 7, v1
	global_load_dwordx4 v[134:137], v7, s[66:67]
	v_lshl_add_u32 v6, v18, 7, v1
	global_load_dwordx4 v[138:141], v6, s[66:67]
	v_lshl_add_u32 v7, v19, 7, v1
	global_load_dwordx4 v[142:145], v7, s[66:67]
	v_lshl_add_u32 v6, v20, 7, v1
	global_load_dwordx4 v[146:149], v6, s[66:67]
	v_lshl_add_u32 v7, v21, 7, v1
	global_load_dwordx4 v[150:153], v7, s[66:67]
	v_lshl_add_u32 v6, v22, 7, v1
	global_load_dwordx4 v[154:157], v6, s[66:67]
	v_lshl_add_u32 v7, v23, 7, v1
	global_load_dwordx4 v[158:161], v7, s[66:67]
	v_lshl_add_u32 v6, v24, 7, v1
	global_load_dwordx4 v[162:165], v6, s[66:67]
	v_lshl_add_u32 v7, v25, 7, v1
	global_load_dwordx4 v[166:169], v7, s[66:67]
	s_lshl_b32 s70, s60, 1
	s_add_u32 s70, s70, s28
	s_lshl_b32 s70, s70, 11
	s_add_u32 s70, s70, s68
	v_add_u32_e32 v8, s70, v0
	global_load_dwordx2 v[26:27], v8, s[76:77]
	s_add_u32 s62, s60, s33
	s_cmp_ge_u32 s62, s61
	s_cbranch_scc1 .Lmy_pu0_pro1
	s_lshl_b32 s70, s62, 10
	v_add_u32_e32 v9, s70, v2
	global_load_dwordx4 v[10:13], v9, s[52:53]
	global_load_dwordx4 v[14:17], v9, s[52:53] offset:16
	global_load_dwordx4 v[18:21], v9, s[52:53] offset:32
	global_load_dwordx4 v[22:25], v9, s[52:53] offset:48

; __device__ __forceinline__ float bflo(unsigned u) { return __uint_as_float(u << 16); }
; __device__ __forceinline__ float bfhi(unsigned u) { return __uint_as_float(u & 0xffff0000u); }
; __device__ __forceinline__ void phase_peer_u(const Params& p, int layer, int xs, int wid0, int wstride, char* smraw) {
;     ...
;   auto compute = [&](int tt, const u32x4 (&q)[16], const u32x2& xv) {
;     const int t = 2 * tt + par;
;     int xq[8]; float sx; int sumx = 0;
;     {
;       const float x0 = bflo(xv[0]), x1 = bfhi(xv[0]), x2 = bflo(xv[1]), x3 = bfhi(xv[1]);
;       float mx = fmaxf(fmaxf(fabsf(x0), fabsf(x1)), fmaxf(fabsf(x2), fabsf(x3)));
; #pragma unroll
;       for (int m = 32; m >= 1; m >>= 1) mx = fmaxf(mx, __shfl_xor(mx, m));
;       const float inv = mx > 0.f ? 127.f / mx : 0.f;
;       sx = mx * (1.f / 127.f);
;       const int q0 = __float2int_rn(x0 * inv), q1 = __float2int_rn(x1 * inv), q2 = __float2int_rn(x2 * inv), q3 = __float2int_rn(x3 * inv);
;       asm volatile("" ::: "memory");
;       *(int*)(xqs + l * 4) = (q0 & 0xff) | ((q1 & 0xff) << 8) | ((q2 & 0xff) << 16) | ((q3 & 0xff) << 24);
;       asm volatile("" ::: "memory");
;       __builtin_amdgcn_wave_barrier();
;       asm volatile("" ::: "memory");
;       const u32x4 xa = *(const u32x4*)(xqs + j * 32), xb = *(const u32x4*)(xqs + j * 32 + 16);
;       asm volatile("" ::: "memory");
; #pragma unroll
;       for (int m = 0; m < 4; ++m) { xq[m] = (int)xa[m]; xq[4 + m] = (int)xb[m]; }
; #pragma unroll
;       for (int m = 0; m < 8; ++m) sumx = __builtin_amdgcn_sdot4(xq[m], 0x01010101, sumx, false);
;     }
;     const int corr = 8 * sumx;
;     float pr[16];
; #pragma unroll
;     for (int i = 0; i < 16; ++i) {
;       int a = 0;
; #pragma unroll
;       for (int m = 0; m < 4; ++m) {
;         const unsigned dw = q[i][m];
;         a = __builtin_amdgcn_sdot4((int)(dw & 0x0f0f0f0fu), xq[2 * m], a, false);
;         a = __builtin_amdgcn_sdot4((int)((dw >> 4) & 0x0f0f0f0fu), xq[2 * m + 1], a, false);
;       }
;       a -= corr;
;       a += __builtin_amdgcn_update_dpp(0, a, 0xB1, 0xF, 0xF, true);
;       a += __builtin_amdgcn_update_dpp(0, a, 0x4E, 0xF, 0xF, true);
;       a += __builtin_amdgcn_update_dpp(0, a, 0x141, 0xF, 0xF, true);
;       pr[i] = (float)a * sx;
.Lmy_pu0_bodyA:
	s_waitcnt vmcnt(4)
	s_add_u32 s62, s60, s33
	s_cmp_ge_u32 s62, s61
	s_cbranch_scc1 .Lmy_pu0_noissueA
	v_lshl_add_u32 v6, v10, 7, v1
	global_load_dwordx4 v[170:173], v6, s[66:67]
	v_lshl_add_u32 v7, v11, 7, v1
	global_load_dwordx4 v[174:177], v7, s[66:67]
	v_lshl_add_u32 v6, v12, 7, v1
	global_load_dwordx4 v[178:181], v6, s[66:67]
	v_lshl_add_u32 v7, v13, 7, v1
	global_load_dwordx4 v[182:185], v7, s[66:67]
	v_lshl_add_u32 v6, v14, 7, v1
	global_load_dwordx4 v[192:195], v6, s[66:67]
	v_lshl_add_u32 v7, v15, 7, v1
	global_load_dwordx4 v[196:199], v7, s[66:67]
	v_lshl_add_u32 v6, v16, 7, v1
	global_load_dwordx4 v[200:203], v6, s[66:67]
	v_lshl_add_u32 v7, v17, 7, v1
	global_load_dwordx4 v[204:207], v7, s[66:67]
	v_lshl_add_u32 v6, v18, 7, v1
	global_load_dwordx4 v[208:211], v6, s[66:67]
	v_lshl_add_u32 v7, v19, 7, v1
	global_load_dwordx4 v[212:215], v7, s[66:67]
	v_lshl_add_u32 v6, v20, 7, v1
	global_load_dwordx4 v[216:219], v6, s[66:67]
	v_lshl_add_u32 v7, v21, 7, v1
	global_load_dwordx4 v[220:223], v7, s[66:67]
	v_lshl_add_u32 v6, v22, 7, v1
	global_load_dwordx4 v[224:227], v6, s[66:67]
	v_lshl_add_u32 v7, v23, 7, v1
	global_load_dwordx4 v[228:231], v7, s[66:67]
	v_lshl_add_u32 v6, v24, 7, v1
	global_load_dwordx4 v[232:235], v6, s[66:67]
	v_lshl_add_u32 v7, v25, 7, v1
	global_load_dwordx4 v[236:239], v7, s[66:67]
	s_lshl_b32 s70, s62, 1
	s_add_u32 s70, s70, s28
	s_lshl_b32 s70, s70, 11
	s_add_u32 s70, s70, s68
	v_add_u32_e32 v8, s70, v0
	global_load_dwordx2 v[28:29], v8, s[76:77]
	s_add_u32 s63, s62, s33
	s_cmp_ge_u32 s63, s61
	s_cbranch_scc1 .Lmy_pu0_noissueA
	s_lshl_b32 s70, s63, 10
	v_add_u32_e32 v9, s70, v2
	global_load_dwordx4 v[10:13], v9, s[52:53]
	global_load_dwordx4 v[14:17], v9, s[52:53] offset:16
	global_load_dwordx4 v[18:21], v9, s[52:53] offset:32
	global_load_dwordx4 v[22:25], v9, s[52:53] offset:48
.Lmy_pu0_noissueA:
	v_lshlrev_b32_e32 v40, 16, v26
	v_and_b32_e32 v41, 0xffff0000, v26
	v_lshlrev_b32_e32 v42, 16, v27
	v_and_b32_e32 v43, 0xffff0000, v27
	v_max_f32_e64 v44, |v40|, |v41|
	v_max3_f32 v44, |v42|, |v43|, v44
	s_nop 1
	v_max_f32_dpp v44, v44, v44 quad_perm:[1,0,3,2] row_mask:0xf bank_mask:0xf bound_ctrl:1
	s_nop 1
	v_max_f32_dpp v44, v44, v44 quad_perm:[2,3,0,1] row_mask:0xf bank_mask:0xf bound_ctrl:1
	s_nop 1
	v_max_f32_dpp v44, v44, v44 row_half_mirror row_mask:0xf bank_mask:0xf bound_ctrl:1
	s_nop 1
	v_max_f32_dpp v44, v44, v44 row_mirror row_mask:0xf bank_mask:0xf bound_ctrl:1
	s_nop 0
	v_readlane_b32 s6, v44, 0
	v_readlane_b32 s7, v44, 16
	v_readlane_b32 s10, v44, 32
	v_readlane_b32 s11, v44, 48
	s_nop 1
	v_mov_b32_e32 v45, s6
	v_max_f32_e32 v45, s7, v45
	v_max_f32_e32 v45, s10, v45
	v_max_f32_e32 v45, s11, v45
	v_div_scale_f32 v46, s[18:19], v45, v45, s69
	v_rcp_f32_e32 v47, v46
	s_nop 0
	v_fma_f32 v48, -v46, v47, 1.0
	v_fmac_f32_e32 v47, v48, v47
	v_div_scale_f32 v48, vcc, s69, v45, s69
	v_mul_f32_e32 v49, v48, v47
	v_fma_f32 v50, -v46, v49, v48
	v_fmac_f32_e32 v49, v50, v47
	v_fma_f32 v46, -v46, v49, v48
	v_div_fmas_f32 v46, v46, v47, v49
	v_div_fixup_f32 v46, v46, v45, s69
	v_cmp_lt_f32_e32 vcc, 0, v45
	v_mul_f32_e32 v52, 0x3c010204, v45
	v_mov_b32_e32 v84, 0
	v_cndmask_b32_e32 v46, 0, v46, vcc
	v_mul_f32_e32 v40, v46, v40
	v_mul_f32_e32 v41, v46, v41
	v_mul_f32_e32 v42, v46, v42
	v_mul_f32_e32 v43, v46, v43
	v_rndne_f32_e32 v40, v40
	v_rndne_f32_e32 v41, v41
	v_rndne_f32_e32 v42, v42
	v_rndne_f32_e32 v43, v43
	v_cvt_i32_f32_e32 v40, v40
	v_cvt_i32_f32_e32 v41, v41
	v_cvt_i32_f32_e32 v42, v42
	v_cvt_i32_f32_e32 v43, v43
	v_and_b32_e32 v40, 0xff, v40
	v_and_b32_e32 v41, 0xff, v41
	v_and_b32_e32 v42, 0xff, v42
	v_lshl_or_b32 v40, v41, 8, v40
	v_lshl_or_b32 v40, v42, 16, v40
	v_lshl_or_b32 v40, v43, 24, v40
	ds_write_b32 v3, v40
	ds_read_b128 v[32:35], v4
	ds_read_b128 v[36:39], v4 offset:16
	s_waitcnt lgkmcnt(0)
	v_dot4c_i32_i8_e32 v84, 0x1010101, v32
	v_dot4c_i32_i8_e32 v84, 0x1010101, v33
	v_dot4c_i32_i8_e32 v84, 0x1010101, v34
	v_dot4c_i32_i8_e32 v84, 0x1010101, v35
	v_dot4c_i32_i8_e32 v84, 0x1010101, v36
	v_dot4c_i32_i8_e32 v84, 0x1010101, v37
	v_dot4c_i32_i8_e32 v84, 0x1010101, v38
	v_dot4c_i32_i8_e32 v84, 0x1010101, v39
	v_and_b32_e32 v56, s21, v106
	v_lshrrev_b32_e32 v57, 4, v106
	v_and_b32_e32 v57, s21, v57
	v_and_b32_e32 v58, s21, v110
	v_lshrrev_b32_e32 v59, 4, v110
	v_and_b32_e32 v59, s21, v59
	v_and_b32_e32 v60, s21, v114
	v_lshrrev_b32_e32 v61, 4, v114
	v_and_b32_e32 v61, s21, v61
	v_and_b32_e32 v62, s21, v118
	v_lshrrev_b32_e32 v63, 4, v118
	v_and_b32_e32 v63, s21, v63
	v_mul_i32_i24_e32 v85, -8, v84
	v_mov_b32_e32 v64, v85
	v_mov_b32_e32 v65, v85
	v_mov_b32_e32 v66, v85
	v_mov_b32_e32 v67, v85
	v_dot4c_i32_i8_e32 v64, v56, v32
	v_dot4c_i32_i8_e32 v64, v57, v33
	v_dot4c_i32_i8_e32 v65, v58, v32
	v_dot4c_i32_i8_e32 v65, v59, v33
	v_dot4c_i32_i8_e32 v66, v60, v32
	v_dot4c_i32_i8_e32 v66, v61, v33
	v_dot4c_i32_i8_e32 v67, v62, v32
	v_dot4c_i32_i8_e32 v67, v63, v33
	v_and_b32_e32 v56, s21, v107
	v_lshrrev_b32_e32 v57, 4, v107
	v_and_b32_e32 v57, s21, v57
	v_and_b32_e32 v58, s21, v111
	v_lshrrev_b32_e32 v59, 4, v111
	v_and_b32_e32 v59, s21, v59
	v_and_b32_e32 v60, s21, v115
	v_lshrrev_b32_e32 v61, 4, v115
	v_and_b32_e32 v61, s21, v61
	v_and_b32_e32 v62, s21, v119
	v_lshrrev_b32_e32 v63, 4, v119
	v_and_b32_e32 v63, s21, v63
	v_dot4c_i32_i8_e32 v64, v56, v34
	v_dot4c_i32_i8_e32 v64, v57, v35
	v_dot4c_i32_i8_e32 v65, v58, v34
	v_dot4c_i32_i8_e32 v65, v59, v35
	v_dot4c_i32_i8_e32 v66, v60, v34
	v_dot4c_i32_i8_e32 v66, v61, v35
	v_dot4c_i32_i8_e32 v67, v62, v34
	v_dot4c_i32_i8_e32 v67, v63, v35
	v_and_b32_e32 v56, s21, v108
	v_lshrrev_b32_e32 v57, 4, v108
	v_and_b32_e32 v57, s21, v57
; __device__ __forceinline__ void phase_peer_u(const Params& p, int layer, int xs, int wid0, int wstride, char* smraw) {
;     ...
;     float pr[16];
; #pragma unroll
;     for (int i = 0; i < 16; ++i) {
;       int a = 0;
; #pragma unroll
;       for (int m = 0; m < 4; ++m) {
;         const unsigned dw = q[i][m];
;         a = __builtin_amdgcn_sdot4((int)(dw & 0x0f0f0f0fu), xq[2 * m], a, false);
;         a = __builtin_amdgcn_sdot4((int)((dw >> 4) & 0x0f0f0f0fu), xq[2 * m + 1], a, false);
;       }
;       a -= corr;
;       a += __builtin_amdgcn_update_dpp(0, a, 0xB1, 0xF, 0xF, true);
;       a += __builtin_amdgcn_update_dpp(0, a, 0x4E, 0xF, 0xF, true);
;       a += __builtin_amdgcn_update_dpp(0, a, 0x141, 0xF, 0xF, true);
;       pr[i] = (float)a * sx;
	v_and_b32_e32 v58, s21, v112
	v_lshrrev_b32_e32 v59, 4, v112
	v_and_b32_e32 v59, s21, v59
	v_and_b32_e32 v60, s21, v116
	v_lshrrev_b32_e32 v61, 4, v116
	v_and_b32_e32 v61, s21, v61
	v_and_b32_e32 v62, s21, v120
	v_lshrrev_b32_e32 v63, 4, v120
	v_and_b32_e32 v63, s21, v63
	v_dot4c_i32_i8_e32 v64, v56, v36
	v_dot4c_i32_i8_e32 v64, v57, v37
	v_dot4c_i32_i8_e32 v65, v58, v36
	v_dot4c_i32_i8_e32 v65, v59, v37
	v_dot4c_i32_i8_e32 v66, v60, v36
	v_dot4c_i32_i8_e32 v66, v61, v37
	v_dot4c_i32_i8_e32 v67, v62, v36
	v_dot4c_i32_i8_e32 v67, v63, v37
	v_and_b32_e32 v56, s21, v109
	v_lshrrev_b32_e32 v57, 4, v109
	v_and_b32_e32 v57, s21, v57
	v_and_b32_e32 v58, s21, v113
	v_lshrrev_b32_e32 v59, 4, v113
	v_and_b32_e32 v59, s21, v59
	v_and_b32_e32 v60, s21, v117
	v_lshrrev_b32_e32 v61, 4, v117
	v_and_b32_e32 v61, s21, v61
	v_and_b32_e32 v62, s21, v121
	v_lshrrev_b32_e32 v63, 4, v121
	v_and_b32_e32 v63, s21, v63
	v_dot4c_i32_i8_e32 v64, v56, v38
	v_dot4c_i32_i8_e32 v64, v57, v39
	v_dot4c_i32_i8_e32 v65, v58, v38
	v_dot4c_i32_i8_e32 v65, v59, v39
	v_dot4c_i32_i8_e32 v66, v60, v38
	v_dot4c_i32_i8_e32 v66, v61, v39
	v_dot4c_i32_i8_e32 v67, v62, v38
	v_dot4c_i32_i8_e32 v67, v63, v39
	v_add_u32_dpp v64, v64, v64 quad_perm:[1,0,3,2] row_mask:0xf bank_mask:0xf bound_ctrl:1
	v_add_u32_dpp v65, v65, v65 quad_perm:[1,0,3,2] row_mask:0xf bank_mask:0xf bound_ctrl:1
	v_add_u32_dpp v66, v66, v66 quad_perm:[1,0,3,2] row_mask:0xf bank_mask:0xf bound_ctrl:1
	v_add_u32_dpp v67, v67, v67 quad_perm:[1,0,3,2] row_mask:0xf bank_mask:0xf bound_ctrl:1
	v_add_u32_dpp v64, v64, v64 quad_perm:[2,3,0,1] row_mask:0xf bank_mask:0xf bound_ctrl:1
	v_add_u32_dpp v65, v65, v65 quad_perm:[2,3,0,1] row_mask:0xf bank_mask:0xf bound_ctrl:1
	v_add_u32_dpp v66, v66, v66 quad_perm:[2,3,0,1] row_mask:0xf bank_mask:0xf bound_ctrl:1
	v_add_u32_dpp v67, v67, v67 quad_perm:[2,3,0,1] row_mask:0xf bank_mask:0xf bound_ctrl:1
	v_add_u32_dpp v64, v64, v64 row_half_mirror row_mask:0xf bank_mask:0xf bound_ctrl:1
	v_add_u32_dpp v65, v65, v65 row_half_mirror row_mask:0xf bank_mask:0xf bound_ctrl:1
	v_add_u32_dpp v66, v66, v66 row_half_mirror row_mask:0xf bank_mask:0xf bound_ctrl:1
	v_add_u32_dpp v67, v67, v67 row_half_mirror row_mask:0xf bank_mask:0xf bound_ctrl:1
	v_cvt_f32_i32_e32 v68, v64
	v_cvt_f32_i32_e32 v69, v65
	v_cvt_f32_i32_e32 v70, v66
	v_cvt_f32_i32_e32 v71, v67
	v_pk_mul_f32 v[68:69], v[52:53], v[68:69] op_sel_hi:[0,1]
	v_pk_mul_f32 v[70:71], v[52:53], v[70:71] op_sel_hi:[0,1]
	v_and_b32_e32 v56, s21, v122
	v_lshrrev_b32_e32 v57, 4, v122
	v_and_b32_e32 v57, s21, v57
	v_and_b32_e32 v58, s21, v126
	v_lshrrev_b32_e32 v59, 4, v126
	v_and_b32_e32 v59, s21, v59
	v_and_b32_e32 v60, s21, v130
	v_lshrrev_b32_e32 v61, 4, v130
	v_and_b32_e32 v61, s21, v61
	v_and_b32_e32 v62, s21, v134
	v_lshrrev_b32_e32 v63, 4, v134
	v_and_b32_e32 v63, s21, v63
	v_mov_b32_e32 v64, v85
	v_mov_b32_e32 v65, v85
	v_mov_b32_e32 v66, v85
	v_mov_b32_e32 v67, v85
	v_dot4c_i32_i8_e32 v64, v56, v32
	v_dot4c_i32_i8_e32 v64, v57, v33
	v_dot4c_i32_i8_e32 v65, v58, v32
	v_dot4c_i32_i8_e32 v65, v59, v33
	v_dot4c_i32_i8_e32 v66, v60, v32
	v_dot4c_i32_i8_e32 v66, v61, v33
	v_dot4c_i32_i8_e32 v67, v62, v32
	v_dot4c_i32_i8_e32 v67, v63, v33
	v_and_b32_e32 v56, s21, v123
	v_lshrrev_b32_e32 v57, 4, v123
	v_and_b32_e32 v57, s21, v57
	v_and_b32_e32 v58, s21, v127
	v_lshrrev_b32_e32 v59, 4, v127
	v_and_b32_e32 v59, s21, v59
	v_and_b32_e32 v60, s21, v131
	v_lshrrev_b32_e32 v61, 4, v131
	v_and_b32_e32 v61, s21, v61
	v_and_b32_e32 v62, s21, v135
	v_lshrrev_b32_e32 v63, 4, v135
	v_and_b32_e32 v63, s21, v63
	v_dot4c_i32_i8_e32 v64, v56, v34
	v_dot4c_i32_i8_e32 v64, v57, v35
	v_dot4c_i32_i8_e32 v65, v58, v34
	v_dot4c_i32_i8_e32 v65, v59, v35
	v_dot4c_i32_i8_e32 v66, v60, v34
	v_dot4c_i32_i8_e32 v66, v61, v35
	v_dot4c_i32_i8_e32 v67, v62, v34
	v_dot4c_i32_i8_e32 v67, v63, v35
	v_and_b32_e32 v56, s21, v124
	v_lshrrev_b32_e32 v57, 4, v124
	v_and_b32_e32 v57, s21, v57
	v_and_b32_e32 v58, s21, v128
	v_lshrrev_b32_e32 v59, 4, v128
	v_and_b32_e32 v59, s21, v59
	v_and_b32_e32 v60, s21, v132
	v_lshrrev_b32_e32 v61, 4, v132
	v_and_b32_e32 v61, s21, v61
	v_and_b32_e32 v62, s21, v136
	v_lshrrev_b32_e32 v63, 4, v136
	v_and_b32_e32 v63, s21, v63
	v_dot4c_i32_i8_e32 v64, v56, v36
	v_dot4c_i32_i8_e32 v64, v57, v37
	v_dot4c_i32_i8_e32 v65, v58, v36
	v_dot4c_i32_i8_e32 v65, v59, v37
	v_dot4c_i32_i8_e32 v66, v60, v36
	v_dot4c_i32_i8_e32 v66, v61, v37
	v_dot4c_i32_i8_e32 v67, v62, v36
	v_dot4c_i32_i8_e32 v67, v63, v37
	v_and_b32_e32 v56, s21, v125
	v_lshrrev_b32_e32 v57, 4, v125
	v_and_b32_e32 v57, s21, v57
	v_and_b32_e32 v58, s21, v129
	v_lshrrev_b32_e32 v59, 4, v129
	v_and_b32_e32 v59, s21, v59
	v_and_b32_e32 v60, s21, v133
	v_lshrrev_b32_e32 v61, 4, v133
	v_and_b32_e32 v61, s21, v61
	v_and_b32_e32 v62, s21, v137
	v_lshrrev_b32_e32 v63, 4, v137
	v_and_b32_e32 v63, s21, v63
	v_dot4c_i32_i8_e32 v64, v56, v38
	v_dot4c_i32_i8_e32 v64, v57, v39
	v_dot4c_i32_i8_e32 v65, v58, v38
	v_dot4c_i32_i8_e32 v65, v59, v39
	v_dot4c_i32_i8_e32 v66, v60, v38
	v_dot4c_i32_i8_e32 v66, v61, v39
	v_dot4c_i32_i8_e32 v67, v62, v38
	v_dot4c_i32_i8_e32 v67, v63, v39
	v_add_u32_dpp v64, v64, v64 quad_perm:[1,0,3,2] row_mask:0xf bank_mask:0xf bound_ctrl:1
	v_add_u32_dpp v65, v65, v65 quad_perm:[1,0,3,2] row_mask:0xf bank_mask:0xf bound_ctrl:1
	v_add_u32_dpp v66, v66, v66 quad_perm:[1,0,3,2] row_mask:0xf bank_mask:0xf bound_ctrl:1
	v_add_u32_dpp v67, v67, v67 quad_perm:[1,0,3,2] row_mask:0xf bank_mask:0xf bound_ctrl:1
	v_add_u32_dpp v64, v64, v64 quad_perm:[2,3,0,1] row_mask:0xf bank_mask:0xf bound_ctrl:1
	v_add_u32_dpp v65, v65, v65 quad_perm:[2,3,0,1] row_mask:0xf bank_mask:0xf bound_ctrl:1
; __device__ __forceinline__ void phase_peer_u(const Params& p, int layer, int xs, int wid0, int wstride, char* smraw) {
;     ...
;     const int corr = 8 * sumx;
;     float pr[16];
; #pragma unroll
;     for (int i = 0; i < 16; ++i) {
;       int a = 0;
; #pragma unroll
;       for (int m = 0; m < 4; ++m) {
;         const unsigned dw = q[i][m];
;         a = __builtin_amdgcn_sdot4((int)(dw & 0x0f0f0f0fu), xq[2 * m], a, false);
;         a = __builtin_amdgcn_sdot4((int)((dw >> 4) & 0x0f0f0f0fu), xq[2 * m + 1], a, false);
;       }
;       a -= corr;
;       a += __builtin_amdgcn_update_dpp(0, a, 0xB1, 0xF, 0xF, true);
;       a += __builtin_amdgcn_update_dpp(0, a, 0x4E, 0xF, 0xF, true);
;       a += __builtin_amdgcn_update_dpp(0, a, 0x141, 0xF, 0xF, true);
;       pr[i] = (float)a * sx;
;     }
	v_add_u32_dpp v66, v66, v66 quad_perm:[2,3,0,1] row_mask:0xf bank_mask:0xf bound_ctrl:1
	v_add_u32_dpp v67, v67, v67 quad_perm:[2,3,0,1] row_mask:0xf bank_mask:0xf bound_ctrl:1
	v_add_u32_dpp v64, v64, v64 row_half_mirror row_mask:0xf bank_mask:0xf bound_ctrl:1
	v_add_u32_dpp v65, v65, v65 row_half_mirror row_mask:0xf bank_mask:0xf bound_ctrl:1
	v_add_u32_dpp v66, v66, v66 row_half_mirror row_mask:0xf bank_mask:0xf bound_ctrl:1
	v_add_u32_dpp v67, v67, v67 row_half_mirror row_mask:0xf bank_mask:0xf bound_ctrl:1
	v_cvt_f32_i32_e32 v72, v64
	v_cvt_f32_i32_e32 v73, v65
	v_cvt_f32_i32_e32 v74, v66
	v_cvt_f32_i32_e32 v75, v67
	v_pk_mul_f32 v[72:73], v[52:53], v[72:73] op_sel_hi:[0,1]
	v_pk_mul_f32 v[74:75], v[52:53], v[74:75] op_sel_hi:[0,1]
	v_and_b32_e32 v56, s21, v138
	v_lshrrev_b32_e32 v57, 4, v138
	v_and_b32_e32 v57, s21, v57
	v_and_b32_e32 v58, s21, v142
	v_lshrrev_b32_e32 v59, 4, v142
	v_and_b32_e32 v59, s21, v59
	v_and_b32_e32 v60, s21, v146
	v_lshrrev_b32_e32 v61, 4, v146
	v_and_b32_e32 v61, s21, v61
	v_and_b32_e32 v62, s21, v150
	v_lshrrev_b32_e32 v63, 4, v150
	v_and_b32_e32 v63, s21, v63
	v_mov_b32_e32 v64, v85
	v_mov_b32_e32 v65, v85
	v_mov_b32_e32 v66, v85
	v_mov_b32_e32 v67, v85
	v_dot4c_i32_i8_e32 v64, v56, v32
	v_dot4c_i32_i8_e32 v64, v57, v33
	v_dot4c_i32_i8_e32 v65, v58, v32
	v_dot4c_i32_i8_e32 v65, v59, v33
	v_dot4c_i32_i8_e32 v66, v60, v32
	v_dot4c_i32_i8_e32 v66, v61, v33
	v_dot4c_i32_i8_e32 v67, v62, v32
	v_dot4c_i32_i8_e32 v67, v63, v33
	v_and_b32_e32 v56, s21, v139
	v_lshrrev_b32_e32 v57, 4, v139
	v_and_b32_e32 v57, s21, v57
	v_and_b32_e32 v58, s21, v143
	v_lshrrev_b32_e32 v59, 4, v143
	v_and_b32_e32 v59, s21, v59
	v_and_b32_e32 v60, s21, v147
	v_lshrrev_b32_e32 v61, 4, v147
	v_and_b32_e32 v61, s21, v61
	v_and_b32_e32 v62, s21, v151
	v_lshrrev_b32_e32 v63, 4, v151
	v_and_b32_e32 v63, s21, v63
	v_dot4c_i32_i8_e32 v64, v56, v34
	v_dot4c_i32_i8_e32 v64, v57, v35
	v_dot4c_i32_i8_e32 v65, v58, v34
	v_dot4c_i32_i8_e32 v65, v59, v35
	v_dot4c_i32_i8_e32 v66, v60, v34
	v_dot4c_i32_i8_e32 v66, v61, v35
	v_dot4c_i32_i8_e32 v67, v62, v34
	v_dot4c_i32_i8_e32 v67, v63, v35
	v_and_b32_e32 v56, s21, v140
	v_lshrrev_b32_e32 v57, 4, v140
	v_and_b32_e32 v57, s21, v57
	v_and_b32_e32 v58, s21, v144
	v_lshrrev_b32_e32 v59, 4, v144
	v_and_b32_e32 v59, s21, v59
	v_and_b32_e32 v60, s21, v148
	v_lshrrev_b32_e32 v61, 4, v148
	v_and_b32_e32 v61, s21, v61
	v_and_b32_e32 v62, s21, v152
	v_lshrrev_b32_e32 v63, 4, v152
	v_and_b32_e32 v63, s21, v63
	v_dot4c_i32_i8_e32 v64, v56, v36
	v_dot4c_i32_i8_e32 v64, v57, v37
	v_dot4c_i32_i8_e32 v65, v58, v36
	v_dot4c_i32_i8_e32 v65, v59, v37
	v_dot4c_i32_i8_e32 v66, v60, v36
	v_dot4c_i32_i8_e32 v66, v61, v37
	v_dot4c_i32_i8_e32 v67, v62, v36
	v_dot4c_i32_i8_e32 v67, v63, v37
	v_and_b32_e32 v56, s21, v141
	v_lshrrev_b32_e32 v57, 4, v141
	v_and_b32_e32 v57, s21, v57
	v_and_b32_e32 v58, s21, v145
	v_lshrrev_b32_e32 v59, 4, v145
	v_and_b32_e32 v59, s21, v59
	v_and_b32_e32 v60, s21, v149
	v_lshrrev_b32_e32 v61, 4, v149
	v_and_b32_e32 v61, s21, v61
	v_and_b32_e32 v62, s21, v153
	v_lshrrev_b32_e32 v63, 4, v153
	v_and_b32_e32 v63, s21, v63
	v_dot4c_i32_i8_e32 v64, v56, v38
	v_dot4c_i32_i8_e32 v64, v57, v39
	v_dot4c_i32_i8_e32 v65, v58, v38
	v_dot4c_i32_i8_e32 v65, v59, v39
	v_dot4c_i32_i8_e32 v66, v60, v38
	v_dot4c_i32_i8_e32 v66, v61, v39
	v_dot4c_i32_i8_e32 v67, v62, v38
	v_dot4c_i32_i8_e32 v67, v63, v39
	v_add_u32_dpp v64, v64, v64 quad_perm:[1,0,3,2] row_mask:0xf bank_mask:0xf bound_ctrl:1
	v_add_u32_dpp v65, v65, v65 quad_perm:[1,0,3,2] row_mask:0xf bank_mask:0xf bound_ctrl:1
	v_add_u32_dpp v66, v66, v66 quad_perm:[1,0,3,2] row_mask:0xf bank_mask:0xf bound_ctrl:1
	v_add_u32_dpp v67, v67, v67 quad_perm:[1,0,3,2] row_mask:0xf bank_mask:0xf bound_ctrl:1
	v_add_u32_dpp v64, v64, v64 quad_perm:[2,3,0,1] row_mask:0xf bank_mask:0xf bound_ctrl:1
	v_add_u32_dpp v65, v65, v65 quad_perm:[2,3,0,1] row_mask:0xf bank_mask:0xf bound_ctrl:1
	v_add_u32_dpp v66, v66, v66 quad_perm:[2,3,0,1] row_mask:0xf bank_mask:0xf bound_ctrl:1
	v_add_u32_dpp v67, v67, v67 quad_perm:[2,3,0,1] row_mask:0xf bank_mask:0xf bound_ctrl:1
	v_add_u32_dpp v64, v64, v64 row_half_mirror row_mask:0xf bank_mask:0xf bound_ctrl:1
	v_add_u32_dpp v65, v65, v65 row_half_mirror row_mask:0xf bank_mask:0xf bound_ctrl:1
	v_add_u32_dpp v66, v66, v66 row_half_mirror row_mask:0xf bank_mask:0xf bound_ctrl:1
	v_add_u32_dpp v67, v67, v67 row_half_mirror row_mask:0xf bank_mask:0xf bound_ctrl:1
	v_cvt_f32_i32_e32 v76, v64
	v_cvt_f32_i32_e32 v77, v65
	v_cvt_f32_i32_e32 v78, v66
	v_cvt_f32_i32_e32 v79, v67
	v_pk_mul_f32 v[76:77], v[52:53], v[76:77] op_sel_hi:[0,1]
	v_pk_mul_f32 v[78:79], v[52:53], v[78:79] op_sel_hi:[0,1]
	v_and_b32_e32 v56, s21, v154
	v_lshrrev_b32_e32 v57, 4, v154
	v_and_b32_e32 v57, s21, v57
	v_and_b32_e32 v58, s21, v158
	v_lshrrev_b32_e32 v59, 4, v158
	v_and_b32_e32 v59, s21, v59
	v_and_b32_e32 v60, s21, v162
	v_lshrrev_b32_e32 v61, 4, v162
	v_and_b32_e32 v61, s21, v61
	v_and_b32_e32 v62, s21, v166
	v_lshrrev_b32_e32 v63, 4, v166
	v_and_b32_e32 v63, s21, v63
	v_mov_b32_e32 v64, v85
	v_mov_b32_e32 v65, v85
	v_mov_b32_e32 v66, v85
	v_mov_b32_e32 v67, v85
	v_dot4c_i32_i8_e32 v64, v56, v32
	v_dot4c_i32_i8_e32 v64, v57, v33
	v_dot4c_i32_i8_e32 v65, v58, v32
	v_dot4c_i32_i8_e32 v65, v59, v33
	v_dot4c_i32_i8_e32 v66, v60, v32
	v_dot4c_i32_i8_e32 v66, v61, v33
	v_dot4c_i32_i8_e32 v67, v62, v32
	v_dot4c_i32_i8_e32 v67, v63, v33
	v_and_b32_e32 v56, s21, v155
	v_lshrrev_b32_e32 v57, 4, v155
	v_and_b32_e32 v57, s21, v57
	v_and_b32_e32 v58, s21, v159
	v_lshrrev_b32_e32 v59, 4, v159
	v_and_b32_e32 v59, s21, v59
	v_and_b32_e32 v60, s21, v163
	v_lshrrev_b32_e32 v61, 4, v163
; __device__ __forceinline__ void phase_peer_u(const Params& p, int layer, int xs, int wid0, int wstride, char* smraw) {
;     ...
;   auto load_idx = [&](int tt) {
;     const u32x4* ip = (const u32x4*)((const char*)p.sel_idx + ((unsigned)(2 * tt + par) * 512u + (unsigned)g * 64u));
; #pragma unroll
;     for (int q4 = 0; q4 < 4; ++q4) ni[q4] = ip[q4];
;   };
;   auto issue_rows = [&](int tt, u32x4 (&q)[16], u32x2& xv) {
; #pragma unroll
;     for (int i = 0; i < 16; ++i) q[i] = *(const u32x4*)(Uq + (ni[i >> 2][i & 3] * 128u + joff));
;     xv = *(const u32x2*)((const char*)p.hb + ((unsigned)(2 * tt + par) * 2048u + (unsigned)(sl * 512 + l * 8)));
;   };
;     ...
; #pragma unroll
;     for (int i = 0; i < 16; ++i) {
;       int a = 0;
; #pragma unroll
;       for (int m = 0; m < 4; ++m) {
;         const unsigned dw = q[i][m];
;         a = __builtin_amdgcn_sdot4((int)(dw & 0x0f0f0f0fu), xq[2 * m], a, false);
;         a = __builtin_amdgcn_sdot4((int)((dw >> 4) & 0x0f0f0f0fu), xq[2 * m + 1], a, false);
;       }
;       a -= corr;
;       a += __builtin_amdgcn_update_dpp(0, a, 0xB1, 0xF, 0xF, true);
;       a += __builtin_amdgcn_update_dpp(0, a, 0x4E, 0xF, 0xF, true);
;       a += __builtin_amdgcn_update_dpp(0, a, 0x141, 0xF, 0xF, true);
;       pr[i] = (float)a * sx;
;     }
;     if (j == 0) {
;       f32x4* dst = (f32x4*)((char*)p.actp + ((unsigned)t * 4096u + (unsigned)(sl * 512 + g * 64)));
; #pragma unroll
;       for (int q4 = 0; q4 < 4; ++q4) dst[q4] = f32x4{pr[q4 * 4], pr[q4 * 4 + 1], pr[q4 * 4 + 2], pr[q4 * 4 + 3]};
;     }
	v_and_b32_e32 v61, s21, v61
	v_and_b32_e32 v62, s21, v167
	v_lshrrev_b32_e32 v63, 4, v167
	v_and_b32_e32 v63, s21, v63
	v_dot4c_i32_i8_e32 v64, v56, v34
	v_dot4c_i32_i8_e32 v64, v57, v35
	v_dot4c_i32_i8_e32 v65, v58, v34
	v_dot4c_i32_i8_e32 v65, v59, v35
	v_dot4c_i32_i8_e32 v66, v60, v34
	v_dot4c_i32_i8_e32 v66, v61, v35
	v_dot4c_i32_i8_e32 v67, v62, v34
	v_dot4c_i32_i8_e32 v67, v63, v35
	v_and_b32_e32 v56, s21, v156
	v_lshrrev_b32_e32 v57, 4, v156
	v_and_b32_e32 v57, s21, v57
	v_and_b32_e32 v58, s21, v160
	v_lshrrev_b32_e32 v59, 4, v160
	v_and_b32_e32 v59, s21, v59
	v_and_b32_e32 v60, s21, v164
	v_lshrrev_b32_e32 v61, 4, v164
	v_and_b32_e32 v61, s21, v61
	v_and_b32_e32 v62, s21, v168
	v_lshrrev_b32_e32 v63, 4, v168
	v_and_b32_e32 v63, s21, v63
	v_dot4c_i32_i8_e32 v64, v56, v36
	v_dot4c_i32_i8_e32 v64, v57, v37
	v_dot4c_i32_i8_e32 v65, v58, v36
	v_dot4c_i32_i8_e32 v65, v59, v37
	v_dot4c_i32_i8_e32 v66, v60, v36
	v_dot4c_i32_i8_e32 v66, v61, v37
	v_dot4c_i32_i8_e32 v67, v62, v36
	v_dot4c_i32_i8_e32 v67, v63, v37
	v_and_b32_e32 v56, s21, v157
	v_lshrrev_b32_e32 v57, 4, v157
	v_and_b32_e32 v57, s21, v57
	v_and_b32_e32 v58, s21, v161
	v_lshrrev_b32_e32 v59, 4, v161
	v_and_b32_e32 v59, s21, v59
	v_and_b32_e32 v60, s21, v165
	v_lshrrev_b32_e32 v61, 4, v165
	v_and_b32_e32 v61, s21, v61
	v_and_b32_e32 v62, s21, v169
	v_lshrrev_b32_e32 v63, 4, v169
	v_and_b32_e32 v63, s21, v63
	v_dot4c_i32_i8_e32 v64, v56, v38
	v_dot4c_i32_i8_e32 v64, v57, v39
	v_dot4c_i32_i8_e32 v65, v58, v38
	v_dot4c_i32_i8_e32 v65, v59, v39
	v_dot4c_i32_i8_e32 v66, v60, v38
	v_dot4c_i32_i8_e32 v66, v61, v39
	v_dot4c_i32_i8_e32 v67, v62, v38
	v_dot4c_i32_i8_e32 v67, v63, v39
	v_add_u32_dpp v64, v64, v64 quad_perm:[1,0,3,2] row_mask:0xf bank_mask:0xf bound_ctrl:1
	v_add_u32_dpp v65, v65, v65 quad_perm:[1,0,3,2] row_mask:0xf bank_mask:0xf bound_ctrl:1
	v_add_u32_dpp v66, v66, v66 quad_perm:[1,0,3,2] row_mask:0xf bank_mask:0xf bound_ctrl:1
	v_add_u32_dpp v67, v67, v67 quad_perm:[1,0,3,2] row_mask:0xf bank_mask:0xf bound_ctrl:1
	v_add_u32_dpp v64, v64, v64 quad_perm:[2,3,0,1] row_mask:0xf bank_mask:0xf bound_ctrl:1
	v_add_u32_dpp v65, v65, v65 quad_perm:[2,3,0,1] row_mask:0xf bank_mask:0xf bound_ctrl:1
	v_add_u32_dpp v66, v66, v66 quad_perm:[2,3,0,1] row_mask:0xf bank_mask:0xf bound_ctrl:1
	v_add_u32_dpp v67, v67, v67 quad_perm:[2,3,0,1] row_mask:0xf bank_mask:0xf bound_ctrl:1
	v_add_u32_dpp v64, v64, v64 row_half_mirror row_mask:0xf bank_mask:0xf bound_ctrl:1
	v_add_u32_dpp v65, v65, v65 row_half_mirror row_mask:0xf bank_mask:0xf bound_ctrl:1
	v_add_u32_dpp v66, v66, v66 row_half_mirror row_mask:0xf bank_mask:0xf bound_ctrl:1
	v_add_u32_dpp v67, v67, v67 row_half_mirror row_mask:0xf bank_mask:0xf bound_ctrl:1
	v_cvt_f32_i32_e32 v80, v64
	v_cvt_f32_i32_e32 v81, v65
	v_cvt_f32_i32_e32 v82, v66
	v_cvt_f32_i32_e32 v83, v67
	v_pk_mul_f32 v[80:81], v[52:53], v[80:81] op_sel_hi:[0,1]
	v_pk_mul_f32 v[82:83], v[52:53], v[82:83] op_sel_hi:[0,1]
	s_lshl_b32 s70, s60, 1
	s_add_u32 s70, s70, s28
	s_lshl_b32 s70, s70, 12
	s_add_u32 s70, s70, s68
	s_mov_b64 s[74:75], exec
	s_and_b64 exec, exec, s[72:73]
	v_add_u32_e32 v9, s70, v5
	global_store_dwordx4 v9, v[68:71], s[64:65]
	global_store_dwordx4 v9, v[72:75], s[64:65] offset:16
	global_store_dwordx4 v9, v[76:79], s[64:65] offset:32
	global_store_dwordx4 v9, v[80:83], s[64:65] offset:48
	s_mov_b64 exec, s[74:75]
	s_mov_b32 s60, s62
	s_cmp_lt_u32 s60, s61
	s_cbranch_scc0 .Lmy_pu0_done
.Lmy_pu0_bodyB:
	s_waitcnt vmcnt(4)
	s_add_u32 s62, s60, s33
	s_cmp_ge_u32 s62, s61
	s_cbranch_scc1 .Lmy_pu0_noissueB
	v_lshl_add_u32 v6, v10, 7, v1
	global_load_dwordx4 v[106:109], v6, s[66:67]
	v_lshl_add_u32 v7, v11, 7, v1
	global_load_dwordx4 v[110:113], v7, s[66:67]
	v_lshl_add_u32 v6, v12, 7, v1
	global_load_dwordx4 v[114:117], v6, s[66:67]
	v_lshl_add_u32 v7, v13, 7, v1
	global_load_dwordx4 v[118:121], v7, s[66:67]
	v_lshl_add_u32 v6, v14, 7, v1
	global_load_dwordx4 v[122:125], v6, s[66:67]
	v_lshl_add_u32 v7, v15, 7, v1
	global_load_dwordx4 v[126:129], v7, s[66:67]
	v_lshl_add_u32 v6, v16, 7, v1
	global_load_dwordx4 v[130:133], v6, s[66:67]
	v_lshl_add_u32 v7, v17, 7, v1
	global_load_dwordx4 v[134:137], v7, s[66:67]
	v_lshl_add_u32 v6, v18, 7, v1
	global_load_dwordx4 v[138:141], v6, s[66:67]
	v_lshl_add_u32 v7, v19, 7, v1
	global_load_dwordx4 v[142:145], v7, s[66:67]
	v_lshl_add_u32 v6, v20, 7, v1
	global_load_dwordx4 v[146:149], v6, s[66:67]
	v_lshl_add_u32 v7, v21, 7, v1
	global_load_dwordx4 v[150:153], v7, s[66:67]
	v_lshl_add_u32 v6, v22, 7, v1
	global_load_dwordx4 v[154:157], v6, s[66:67]
	v_lshl_add_u32 v7, v23, 7, v1
	global_load_dwordx4 v[158:161], v7, s[66:67]
	v_lshl_add_u32 v6, v24, 7, v1
	global_load_dwordx4 v[162:165], v6, s[66:67]
	v_lshl_add_u32 v7, v25, 7, v1
	global_load_dwordx4 v[166:169], v7, s[66:67]
	s_lshl_b32 s70, s62, 1
	s_add_u32 s70, s70, s28
	s_lshl_b32 s70, s70, 11
	s_add_u32 s70, s70, s68
	v_add_u32_e32 v8, s70, v0
	global_load_dwordx2 v[26:27], v8, s[76:77]
	s_add_u32 s63, s62, s33
	s_cmp_ge_u32 s63, s61
	s_cbranch_scc1 .Lmy_pu0_noissueB
	s_lshl_b32 s70, s63, 10
	v_add_u32_e32 v9, s70, v2
	global_load_dwordx4 v[10:13], v9, s[52:53]
	global_load_dwordx4 v[14:17], v9, s[52:53] offset:16
	global_load_dwordx4 v[18:21], v9, s[52:53] offset:32
	global_load_dwordx4 v[22:25], v9, s[52:53] offset:48
; __device__ __forceinline__ float bflo(unsigned u) { return __uint_as_float(u << 16); }
; __device__ __forceinline__ float bfhi(unsigned u) { return __uint_as_float(u & 0xffff0000u); }
; __device__ __forceinline__ void phase_peer_u(const Params& p, int layer, int xs, int wid0, int wstride, char* smraw) {
;     ...
;     int xq[8]; float sx; int sumx = 0;
;     {
;       const float x0 = bflo(xv[0]), x1 = bfhi(xv[0]), x2 = bflo(xv[1]), x3 = bfhi(xv[1]);
;       float mx = fmaxf(fmaxf(fabsf(x0), fabsf(x1)), fmaxf(fabsf(x2), fabsf(x3)));
; #pragma unroll
;       for (int m = 32; m >= 1; m >>= 1) mx = fmaxf(mx, __shfl_xor(mx, m));
;       const float inv = mx > 0.f ? 127.f / mx : 0.f;
;       sx = mx * (1.f / 127.f);
;       const int q0 = __float2int_rn(x0 * inv), q1 = __float2int_rn(x1 * inv), q2 = __float2int_rn(x2 * inv), q3 = __float2int_rn(x3 * inv);
;       asm volatile("" ::: "memory");
;       *(int*)(xqs + l * 4) = (q0 & 0xff) | ((q1 & 0xff) << 8) | ((q2 & 0xff) << 16) | ((q3 & 0xff) << 24);
;       asm volatile("" ::: "memory");
;       __builtin_amdgcn_wave_barrier();
;       asm volatile("" ::: "memory");
;       const u32x4 xa = *(const u32x4*)(xqs + j * 32), xb = *(const u32x4*)(xqs + j * 32 + 16);
;       asm volatile("" ::: "memory");
; #pragma unroll
;       for (int m = 0; m < 4; ++m) { xq[m] = (int)xa[m]; xq[4 + m] = (int)xb[m]; }
; #pragma unroll
;       for (int m = 0; m < 8; ++m) sumx = __builtin_amdgcn_sdot4(xq[m], 0x01010101, sumx, false);
;     }
;     const int corr = 8 * sumx;
;     float pr[16];
; #pragma unroll
;     for (int i = 0; i < 16; ++i) {
;       int a = 0;
; #pragma unroll
;       for (int m = 0; m < 4; ++m) {
;         const unsigned dw = q[i][m];
;         a = __builtin_amdgcn_sdot4((int)(dw & 0x0f0f0f0fu), xq[2 * m], a, false);
;         a = __builtin_amdgcn_sdot4((int)((dw >> 4) & 0x0f0f0f0fu), xq[2 * m + 1], a, false);
;       }
;       a -= corr;
;       a += __builtin_amdgcn_update_dpp(0, a, 0xB1, 0xF, 0xF, true);
;       a += __builtin_amdgcn_update_dpp(0, a, 0x4E, 0xF, 0xF, true);
;       a += __builtin_amdgcn_update_dpp(0, a, 0x141, 0xF, 0xF, true);
;       pr[i] = (float)a * sx;
;     }
.Lmy_pu0_noissueB:
	v_lshlrev_b32_e32 v40, 16, v28
	v_and_b32_e32 v41, 0xffff0000, v28
	v_lshlrev_b32_e32 v42, 16, v29
	v_and_b32_e32 v43, 0xffff0000, v29
	v_max_f32_e64 v44, |v40|, |v41|
	v_max3_f32 v44, |v42|, |v43|, v44
	s_nop 1
	v_max_f32_dpp v44, v44, v44 quad_perm:[1,0,3,2] row_mask:0xf bank_mask:0xf bound_ctrl:1
	s_nop 1
	v_max_f32_dpp v44, v44, v44 quad_perm:[2,3,0,1] row_mask:0xf bank_mask:0xf bound_ctrl:1
	s_nop 1
	v_max_f32_dpp v44, v44, v44 row_half_mirror row_mask:0xf bank_mask:0xf bound_ctrl:1
	s_nop 1
	v_max_f32_dpp v44, v44, v44 row_mirror row_mask:0xf bank_mask:0xf bound_ctrl:1
	s_nop 0
	v_readlane_b32 s6, v44, 0
	v_readlane_b32 s7, v44, 16
	v_readlane_b32 s10, v44, 32
	v_readlane_b32 s11, v44, 48
	s_nop 1
	v_mov_b32_e32 v45, s6
	v_max_f32_e32 v45, s7, v45
	v_max_f32_e32 v45, s10, v45
	v_max_f32_e32 v45, s11, v45
	v_div_scale_f32 v46, s[18:19], v45, v45, s69
	v_rcp_f32_e32 v47, v46
	s_nop 0
	v_fma_f32 v48, -v46, v47, 1.0
	v_fmac_f32_e32 v47, v48, v47
	v_div_scale_f32 v48, vcc, s69, v45, s69
	v_mul_f32_e32 v49, v48, v47
	v_fma_f32 v50, -v46, v49, v48
	v_fmac_f32_e32 v49, v50, v47
	v_fma_f32 v46, -v46, v49, v48
	v_div_fmas_f32 v46, v46, v47, v49
	v_div_fixup_f32 v46, v46, v45, s69
	v_cmp_lt_f32_e32 vcc, 0, v45
	v_mul_f32_e32 v52, 0x3c010204, v45
	v_mov_b32_e32 v84, 0
	v_cndmask_b32_e32 v46, 0, v46, vcc
	v_mul_f32_e32 v40, v46, v40
	v_mul_f32_e32 v41, v46, v41
	v_mul_f32_e32 v42, v46, v42
	v_mul_f32_e32 v43, v46, v43
	v_rndne_f32_e32 v40, v40
	v_rndne_f32_e32 v41, v41
	v_rndne_f32_e32 v42, v42
	v_rndne_f32_e32 v43, v43
	v_cvt_i32_f32_e32 v40, v40
	v_cvt_i32_f32_e32 v41, v41
	v_cvt_i32_f32_e32 v42, v42
	v_cvt_i32_f32_e32 v43, v43
	v_and_b32_e32 v40, 0xff, v40
	v_and_b32_e32 v41, 0xff, v41
	v_and_b32_e32 v42, 0xff, v42
	v_lshl_or_b32 v40, v41, 8, v40
	v_lshl_or_b32 v40, v42, 16, v40
	v_lshl_or_b32 v40, v43, 24, v40
	ds_write_b32 v3, v40
	ds_read_b128 v[32:35], v4
	ds_read_b128 v[36:39], v4 offset:16
	s_waitcnt lgkmcnt(0)
	v_dot4c_i32_i8_e32 v84, 0x1010101, v32
	v_dot4c_i32_i8_e32 v84, 0x1010101, v33
	v_dot4c_i32_i8_e32 v84, 0x1010101, v34
	v_dot4c_i32_i8_e32 v84, 0x1010101, v35
	v_dot4c_i32_i8_e32 v84, 0x1010101, v36
	v_dot4c_i32_i8_e32 v84, 0x1010101, v37
	v_dot4c_i32_i8_e32 v84, 0x1010101, v38
	v_dot4c_i32_i8_e32 v84, 0x1010101, v39
	v_and_b32_e32 v56, s21, v170
	v_lshrrev_b32_e32 v57, 4, v170
	v_and_b32_e32 v57, s21, v57
	v_and_b32_e32 v58, s21, v174
	v_lshrrev_b32_e32 v59, 4, v174
	v_and_b32_e32 v59, s21, v59
	v_and_b32_e32 v60, s21, v178
	v_lshrrev_b32_e32 v61, 4, v178
	v_and_b32_e32 v61, s21, v61
	v_and_b32_e32 v62, s21, v182
	v_lshrrev_b32_e32 v63, 4, v182
	v_and_b32_e32 v63, s21, v63
	v_mul_i32_i24_e32 v85, -8, v84
	v_mov_b32_e32 v64, v85
	v_mov_b32_e32 v65, v85
	v_mov_b32_e32 v66, v85
	v_mov_b32_e32 v67, v85
	v_dot4c_i32_i8_e32 v64, v56, v32
	v_dot4c_i32_i8_e32 v64, v57, v33
	v_dot4c_i32_i8_e32 v65, v58, v32
	v_dot4c_i32_i8_e32 v65, v59, v33
	v_dot4c_i32_i8_e32 v66, v60, v32
	v_dot4c_i32_i8_e32 v66, v61, v33
	v_dot4c_i32_i8_e32 v67, v62, v32
	v_dot4c_i32_i8_e32 v67, v63, v33
	v_and_b32_e32 v56, s21, v171
	v_lshrrev_b32_e32 v57, 4, v171
	v_and_b32_e32 v57, s21, v57
	v_and_b32_e32 v58, s21, v175
	v_lshrrev_b32_e32 v59, 4, v175
	v_and_b32_e32 v59, s21, v59
	v_and_b32_e32 v60, s21, v179
	v_lshrrev_b32_e32 v61, 4, v179
	v_and_b32_e32 v61, s21, v61
	v_and_b32_e32 v62, s21, v183
	v_lshrrev_b32_e32 v63, 4, v183
	v_and_b32_e32 v63, s21, v63
	v_dot4c_i32_i8_e32 v64, v56, v34
	v_dot4c_i32_i8_e32 v64, v57, v35
	v_dot4c_i32_i8_e32 v65, v58, v34
	v_dot4c_i32_i8_e32 v65, v59, v35
	v_dot4c_i32_i8_e32 v66, v60, v34
	v_dot4c_i32_i8_e32 v66, v61, v35
	v_dot4c_i32_i8_e32 v67, v62, v34
	v_dot4c_i32_i8_e32 v67, v63, v35
	v_and_b32_e32 v56, s21, v172
	v_lshrrev_b32_e32 v57, 4, v172
	v_and_b32_e32 v57, s21, v57
	v_and_b32_e32 v58, s21, v176
	v_lshrrev_b32_e32 v59, 4, v176
	v_and_b32_e32 v59, s21, v59
	v_and_b32_e32 v60, s21, v180
	v_lshrrev_b32_e32 v61, 4, v180
	v_and_b32_e32 v61, s21, v61
	v_and_b32_e32 v62, s21, v184
	v_lshrrev_b32_e32 v63, 4, v184
	v_and_b32_e32 v63, s21, v63
	v_dot4c_i32_i8_e32 v64, v56, v36
	v_dot4c_i32_i8_e32 v64, v57, v37
	v_dot4c_i32_i8_e32 v65, v58, v36
	v_dot4c_i32_i8_e32 v65, v59, v37
	v_dot4c_i32_i8_e32 v66, v60, v36
	v_dot4c_i32_i8_e32 v66, v61, v37
	v_dot4c_i32_i8_e32 v67, v62, v36
	v_dot4c_i32_i8_e32 v67, v63, v37
	v_and_b32_e32 v56, s21, v173
	v_lshrrev_b32_e32 v57, 4, v173
	v_and_b32_e32 v57, s21, v57
	v_and_b32_e32 v58, s21, v177
	v_lshrrev_b32_e32 v59, 4, v177
	v_and_b32_e32 v59, s21, v59
	v_and_b32_e32 v60, s21, v181
	v_lshrrev_b32_e32 v61, 4, v181
	v_and_b32_e32 v61, s21, v61
	v_and_b32_e32 v62, s21, v185
	v_lshrrev_b32_e32 v63, 4, v185
	v_and_b32_e32 v63, s21, v63
	v_dot4c_i32_i8_e32 v64, v56, v38
	v_dot4c_i32_i8_e32 v64, v57, v39
	v_dot4c_i32_i8_e32 v65, v58, v38
	v_dot4c_i32_i8_e32 v65, v59, v39
	v_dot4c_i32_i8_e32 v66, v60, v38
	v_dot4c_i32_i8_e32 v66, v61, v39
	v_dot4c_i32_i8_e32 v67, v62, v38
	v_dot4c_i32_i8_e32 v67, v63, v39
	v_add_u32_dpp v64, v64, v64 quad_perm:[1,0,3,2] row_mask:0xf bank_mask:0xf bound_ctrl:1
	v_add_u32_dpp v65, v65, v65 quad_perm:[1,0,3,2] row_mask:0xf bank_mask:0xf bound_ctrl:1
	v_add_u32_dpp v66, v66, v66 quad_perm:[1,0,3,2] row_mask:0xf bank_mask:0xf bound_ctrl:1
	v_add_u32_dpp v67, v67, v67 quad_perm:[1,0,3,2] row_mask:0xf bank_mask:0xf bound_ctrl:1
	v_add_u32_dpp v64, v64, v64 quad_perm:[2,3,0,1] row_mask:0xf bank_mask:0xf bound_ctrl:1
	v_add_u32_dpp v65, v65, v65 quad_perm:[2,3,0,1] row_mask:0xf bank_mask:0xf bound_ctrl:1
	v_add_u32_dpp v66, v66, v66 quad_perm:[2,3,0,1] row_mask:0xf bank_mask:0xf bound_ctrl:1
	v_add_u32_dpp v67, v67, v67 quad_perm:[2,3,0,1] row_mask:0xf bank_mask:0xf bound_ctrl:1
; __device__ __forceinline__ void phase_peer_u(const Params& p, int layer, int xs, int wid0, int wstride, char* smraw) {
;     ...
; #pragma unroll
;     for (int i = 0; i < 16; ++i) {
;       int a = 0;
; #pragma unroll
;       for (int m = 0; m < 4; ++m) {
;         const unsigned dw = q[i][m];
;         a = __builtin_amdgcn_sdot4((int)(dw & 0x0f0f0f0fu), xq[2 * m], a, false);
;         a = __builtin_amdgcn_sdot4((int)((dw >> 4) & 0x0f0f0f0fu), xq[2 * m + 1], a, false);
;       }
;       a -= corr;
;       a += __builtin_amdgcn_update_dpp(0, a, 0xB1, 0xF, 0xF, true);
;       a += __builtin_amdgcn_update_dpp(0, a, 0x4E, 0xF, 0xF, true);
;       a += __builtin_amdgcn_update_dpp(0, a, 0x141, 0xF, 0xF, true);
;       pr[i] = (float)a * sx;
;     }
	v_add_u32_dpp v64, v64, v64 row_half_mirror row_mask:0xf bank_mask:0xf bound_ctrl:1
	v_add_u32_dpp v65, v65, v65 row_half_mirror row_mask:0xf bank_mask:0xf bound_ctrl:1
	v_add_u32_dpp v66, v66, v66 row_half_mirror row_mask:0xf bank_mask:0xf bound_ctrl:1
	v_add_u32_dpp v67, v67, v67 row_half_mirror row_mask:0xf bank_mask:0xf bound_ctrl:1
	v_cvt_f32_i32_e32 v68, v64
	v_cvt_f32_i32_e32 v69, v65
	v_cvt_f32_i32_e32 v70, v66
	v_cvt_f32_i32_e32 v71, v67
	v_pk_mul_f32 v[68:69], v[52:53], v[68:69] op_sel_hi:[0,1]
	v_pk_mul_f32 v[70:71], v[52:53], v[70:71] op_sel_hi:[0,1]
	v_and_b32_e32 v56, s21, v192
	v_lshrrev_b32_e32 v57, 4, v192
	v_and_b32_e32 v57, s21, v57
	v_and_b32_e32 v58, s21, v196
	v_lshrrev_b32_e32 v59, 4, v196
	v_and_b32_e32 v59, s21, v59
	v_and_b32_e32 v60, s21, v200
	v_lshrrev_b32_e32 v61, 4, v200
	v_and_b32_e32 v61, s21, v61
	v_and_b32_e32 v62, s21, v204
	v_lshrrev_b32_e32 v63, 4, v204
	v_and_b32_e32 v63, s21, v63
	v_mov_b32_e32 v64, v85
	v_mov_b32_e32 v65, v85
	v_mov_b32_e32 v66, v85
	v_mov_b32_e32 v67, v85
	v_dot4c_i32_i8_e32 v64, v56, v32
	v_dot4c_i32_i8_e32 v64, v57, v33
	v_dot4c_i32_i8_e32 v65, v58, v32
	v_dot4c_i32_i8_e32 v65, v59, v33
	v_dot4c_i32_i8_e32 v66, v60, v32
	v_dot4c_i32_i8_e32 v66, v61, v33
	v_dot4c_i32_i8_e32 v67, v62, v32
	v_dot4c_i32_i8_e32 v67, v63, v33
	v_and_b32_e32 v56, s21, v193
	v_lshrrev_b32_e32 v57, 4, v193
	v_and_b32_e32 v57, s21, v57
	v_and_b32_e32 v58, s21, v197
	v_lshrrev_b32_e32 v59, 4, v197
	v_and_b32_e32 v59, s21, v59
	v_and_b32_e32 v60, s21, v201
	v_lshrrev_b32_e32 v61, 4, v201
	v_and_b32_e32 v61, s21, v61
	v_and_b32_e32 v62, s21, v205
	v_lshrrev_b32_e32 v63, 4, v205
	v_and_b32_e32 v63, s21, v63
	v_dot4c_i32_i8_e32 v64, v56, v34
	v_dot4c_i32_i8_e32 v64, v57, v35
	v_dot4c_i32_i8_e32 v65, v58, v34
	v_dot4c_i32_i8_e32 v65, v59, v35
	v_dot4c_i32_i8_e32 v66, v60, v34
	v_dot4c_i32_i8_e32 v66, v61, v35
	v_dot4c_i32_i8_e32 v67, v62, v34
	v_dot4c_i32_i8_e32 v67, v63, v35
	v_and_b32_e32 v56, s21, v194
	v_lshrrev_b32_e32 v57, 4, v194
	v_and_b32_e32 v57, s21, v57
	v_and_b32_e32 v58, s21, v198
	v_lshrrev_b32_e32 v59, 4, v198
	v_and_b32_e32 v59, s21, v59
	v_and_b32_e32 v60, s21, v202
	v_lshrrev_b32_e32 v61, 4, v202
	v_and_b32_e32 v61, s21, v61
	v_and_b32_e32 v62, s21, v206
	v_lshrrev_b32_e32 v63, 4, v206
	v_and_b32_e32 v63, s21, v63
	v_dot4c_i32_i8_e32 v64, v56, v36
	v_dot4c_i32_i8_e32 v64, v57, v37
	v_dot4c_i32_i8_e32 v65, v58, v36
	v_dot4c_i32_i8_e32 v65, v59, v37
	v_dot4c_i32_i8_e32 v66, v60, v36
	v_dot4c_i32_i8_e32 v66, v61, v37
	v_dot4c_i32_i8_e32 v67, v62, v36
	v_dot4c_i32_i8_e32 v67, v63, v37
	v_and_b32_e32 v56, s21, v195
	v_lshrrev_b32_e32 v57, 4, v195
	v_and_b32_e32 v57, s21, v57
	v_and_b32_e32 v58, s21, v199
	v_lshrrev_b32_e32 v59, 4, v199
	v_and_b32_e32 v59, s21, v59
	v_and_b32_e32 v60, s21, v203
	v_lshrrev_b32_e32 v61, 4, v203
	v_and_b32_e32 v61, s21, v61
	v_and_b32_e32 v62, s21, v207
	v_lshrrev_b32_e32 v63, 4, v207
	v_and_b32_e32 v63, s21, v63
	v_dot4c_i32_i8_e32 v64, v56, v38
	v_dot4c_i32_i8_e32 v64, v57, v39
	v_dot4c_i32_i8_e32 v65, v58, v38
	v_dot4c_i32_i8_e32 v65, v59, v39
	v_dot4c_i32_i8_e32 v66, v60, v38
	v_dot4c_i32_i8_e32 v66, v61, v39
	v_dot4c_i32_i8_e32 v67, v62, v38
	v_dot4c_i32_i8_e32 v67, v63, v39
	v_add_u32_dpp v64, v64, v64 quad_perm:[1,0,3,2] row_mask:0xf bank_mask:0xf bound_ctrl:1
	v_add_u32_dpp v65, v65, v65 quad_perm:[1,0,3,2] row_mask:0xf bank_mask:0xf bound_ctrl:1
	v_add_u32_dpp v66, v66, v66 quad_perm:[1,0,3,2] row_mask:0xf bank_mask:0xf bound_ctrl:1
	v_add_u32_dpp v67, v67, v67 quad_perm:[1,0,3,2] row_mask:0xf bank_mask:0xf bound_ctrl:1
	v_add_u32_dpp v64, v64, v64 quad_perm:[2,3,0,1] row_mask:0xf bank_mask:0xf bound_ctrl:1
	v_add_u32_dpp v65, v65, v65 quad_perm:[2,3,0,1] row_mask:0xf bank_mask:0xf bound_ctrl:1
	v_add_u32_dpp v66, v66, v66 quad_perm:[2,3,0,1] row_mask:0xf bank_mask:0xf bound_ctrl:1
	v_add_u32_dpp v67, v67, v67 quad_perm:[2,3,0,1] row_mask:0xf bank_mask:0xf bound_ctrl:1
	v_add_u32_dpp v64, v64, v64 row_half_mirror row_mask:0xf bank_mask:0xf bound_ctrl:1
	v_add_u32_dpp v65, v65, v65 row_half_mirror row_mask:0xf bank_mask:0xf bound_ctrl:1
	v_add_u32_dpp v66, v66, v66 row_half_mirror row_mask:0xf bank_mask:0xf bound_ctrl:1
	v_add_u32_dpp v67, v67, v67 row_half_mirror row_mask:0xf bank_mask:0xf bound_ctrl:1
	v_cvt_f32_i32_e32 v72, v64
	v_cvt_f32_i32_e32 v73, v65
	v_cvt_f32_i32_e32 v74, v66
	v_cvt_f32_i32_e32 v75, v67
	v_pk_mul_f32 v[72:73], v[52:53], v[72:73] op_sel_hi:[0,1]
	v_pk_mul_f32 v[74:75], v[52:53], v[74:75] op_sel_hi:[0,1]
	v_and_b32_e32 v56, s21, v208
	v_lshrrev_b32_e32 v57, 4, v208
	v_and_b32_e32 v57, s21, v57
	v_and_b32_e32 v58, s21, v212
	v_lshrrev_b32_e32 v59, 4, v212
	v_and_b32_e32 v59, s21, v59
	v_and_b32_e32 v60, s21, v216
	v_lshrrev_b32_e32 v61, 4, v216
	v_and_b32_e32 v61, s21, v61
	v_and_b32_e32 v62, s21, v220
	v_lshrrev_b32_e32 v63, 4, v220
	v_and_b32_e32 v63, s21, v63
	v_mov_b32_e32 v64, v85
	v_mov_b32_e32 v65, v85
	v_mov_b32_e32 v66, v85
	v_mov_b32_e32 v67, v85
	v_dot4c_i32_i8_e32 v64, v56, v32
	v_dot4c_i32_i8_e32 v64, v57, v33
	v_dot4c_i32_i8_e32 v65, v58, v32
	v_dot4c_i32_i8_e32 v65, v59, v33
	v_dot4c_i32_i8_e32 v66, v60, v32
	v_dot4c_i32_i8_e32 v66, v61, v33
	v_dot4c_i32_i8_e32 v67, v62, v32
	v_dot4c_i32_i8_e32 v67, v63, v33
	v_and_b32_e32 v56, s21, v209
	v_lshrrev_b32_e32 v57, 4, v209
	v_and_b32_e32 v57, s21, v57
	v_and_b32_e32 v58, s21, v213
	v_lshrrev_b32_e32 v59, 4, v213
	v_and_b32_e32 v59, s21, v59
	v_and_b32_e32 v60, s21, v217
	v_lshrrev_b32_e32 v61, 4, v217
	v_and_b32_e32 v61, s21, v61
	v_and_b32_e32 v62, s21, v221
	v_lshrrev_b32_e32 v63, 4, v221
	v_and_b32_e32 v63, s21, v63
	v_dot4c_i32_i8_e32 v64, v56, v34
	v_dot4c_i32_i8_e32 v64, v57, v35
; __device__ __forceinline__ void phase_peer_u(const Params& p, int layer, int xs, int wid0, int wstride, char* smraw) {
;     ...
; #pragma unroll
;     for (int i = 0; i < 16; ++i) {
;       int a = 0;
; #pragma unroll
;       for (int m = 0; m < 4; ++m) {
;         const unsigned dw = q[i][m];
;         a = __builtin_amdgcn_sdot4((int)(dw & 0x0f0f0f0fu), xq[2 * m], a, false);
;         a = __builtin_amdgcn_sdot4((int)((dw >> 4) & 0x0f0f0f0fu), xq[2 * m + 1], a, false);
;       }
;       a -= corr;
;       a += __builtin_amdgcn_update_dpp(0, a, 0xB1, 0xF, 0xF, true);
;       a += __builtin_amdgcn_update_dpp(0, a, 0x4E, 0xF, 0xF, true);
;       a += __builtin_amdgcn_update_dpp(0, a, 0x141, 0xF, 0xF, true);
;       pr[i] = (float)a * sx;
;     }
	v_dot4c_i32_i8_e32 v65, v58, v34
	v_dot4c_i32_i8_e32 v65, v59, v35
	v_dot4c_i32_i8_e32 v66, v60, v34
	v_dot4c_i32_i8_e32 v66, v61, v35
	v_dot4c_i32_i8_e32 v67, v62, v34
	v_dot4c_i32_i8_e32 v67, v63, v35
	v_and_b32_e32 v56, s21, v210
	v_lshrrev_b32_e32 v57, 4, v210
	v_and_b32_e32 v57, s21, v57
	v_and_b32_e32 v58, s21, v214
	v_lshrrev_b32_e32 v59, 4, v214
	v_and_b32_e32 v59, s21, v59
	v_and_b32_e32 v60, s21, v218
	v_lshrrev_b32_e32 v61, 4, v218
	v_and_b32_e32 v61, s21, v61
	v_and_b32_e32 v62, s21, v222
	v_lshrrev_b32_e32 v63, 4, v222
	v_and_b32_e32 v63, s21, v63
	v_dot4c_i32_i8_e32 v64, v56, v36
	v_dot4c_i32_i8_e32 v64, v57, v37
	v_dot4c_i32_i8_e32 v65, v58, v36
	v_dot4c_i32_i8_e32 v65, v59, v37
	v_dot4c_i32_i8_e32 v66, v60, v36
	v_dot4c_i32_i8_e32 v66, v61, v37
	v_dot4c_i32_i8_e32 v67, v62, v36
	v_dot4c_i32_i8_e32 v67, v63, v37
	v_and_b32_e32 v56, s21, v211
	v_lshrrev_b32_e32 v57, 4, v211
	v_and_b32_e32 v57, s21, v57
	v_and_b32_e32 v58, s21, v215
	v_lshrrev_b32_e32 v59, 4, v215
	v_and_b32_e32 v59, s21, v59
	v_and_b32_e32 v60, s21, v219
	v_lshrrev_b32_e32 v61, 4, v219
	v_and_b32_e32 v61, s21, v61
	v_and_b32_e32 v62, s21, v223
	v_lshrrev_b32_e32 v63, 4, v223
	v_and_b32_e32 v63, s21, v63
	v_dot4c_i32_i8_e32 v64, v56, v38
	v_dot4c_i32_i8_e32 v64, v57, v39
	v_dot4c_i32_i8_e32 v65, v58, v38
	v_dot4c_i32_i8_e32 v65, v59, v39
	v_dot4c_i32_i8_e32 v66, v60, v38
	v_dot4c_i32_i8_e32 v66, v61, v39
	v_dot4c_i32_i8_e32 v67, v62, v38
	v_dot4c_i32_i8_e32 v67, v63, v39
	v_add_u32_dpp v64, v64, v64 quad_perm:[1,0,3,2] row_mask:0xf bank_mask:0xf bound_ctrl:1
	v_add_u32_dpp v65, v65, v65 quad_perm:[1,0,3,2] row_mask:0xf bank_mask:0xf bound_ctrl:1
	v_add_u32_dpp v66, v66, v66 quad_perm:[1,0,3,2] row_mask:0xf bank_mask:0xf bound_ctrl:1
	v_add_u32_dpp v67, v67, v67 quad_perm:[1,0,3,2] row_mask:0xf bank_mask:0xf bound_ctrl:1
	v_add_u32_dpp v64, v64, v64 quad_perm:[2,3,0,1] row_mask:0xf bank_mask:0xf bound_ctrl:1
	v_add_u32_dpp v65, v65, v65 quad_perm:[2,3,0,1] row_mask:0xf bank_mask:0xf bound_ctrl:1
	v_add_u32_dpp v66, v66, v66 quad_perm:[2,3,0,1] row_mask:0xf bank_mask:0xf bound_ctrl:1
	v_add_u32_dpp v67, v67, v67 quad_perm:[2,3,0,1] row_mask:0xf bank_mask:0xf bound_ctrl:1
	v_add_u32_dpp v64, v64, v64 row_half_mirror row_mask:0xf bank_mask:0xf bound_ctrl:1
	v_add_u32_dpp v65, v65, v65 row_half_mirror row_mask:0xf bank_mask:0xf bound_ctrl:1
	v_add_u32_dpp v66, v66, v66 row_half_mirror row_mask:0xf bank_mask:0xf bound_ctrl:1
	v_add_u32_dpp v67, v67, v67 row_half_mirror row_mask:0xf bank_mask:0xf bound_ctrl:1
	v_cvt_f32_i32_e32 v76, v64
	v_cvt_f32_i32_e32 v77, v65
	v_cvt_f32_i32_e32 v78, v66
	v_cvt_f32_i32_e32 v79, v67
	v_pk_mul_f32 v[76:77], v[52:53], v[76:77] op_sel_hi:[0,1]
	v_pk_mul_f32 v[78:79], v[52:53], v[78:79] op_sel_hi:[0,1]
	v_and_b32_e32 v56, s21, v224
	v_lshrrev_b32_e32 v57, 4, v224
	v_and_b32_e32 v57, s21, v57
	v_and_b32_e32 v58, s21, v228
	v_lshrrev_b32_e32 v59, 4, v228
	v_and_b32_e32 v59, s21, v59
	v_and_b32_e32 v60, s21, v232
	v_lshrrev_b32_e32 v61, 4, v232
	v_and_b32_e32 v61, s21, v61
	v_and_b32_e32 v62, s21, v236
	v_lshrrev_b32_e32 v63, 4, v236
	v_and_b32_e32 v63, s21, v63
	v_mov_b32_e32 v64, v85
	v_mov_b32_e32 v65, v85
	v_mov_b32_e32 v66, v85
	v_mov_b32_e32 v67, v85
	v_dot4c_i32_i8_e32 v64, v56, v32
	v_dot4c_i32_i8_e32 v64, v57, v33
	v_dot4c_i32_i8_e32 v65, v58, v32
	v_dot4c_i32_i8_e32 v65, v59, v33
	v_dot4c_i32_i8_e32 v66, v60, v32
	v_dot4c_i32_i8_e32 v66, v61, v33
	v_dot4c_i32_i8_e32 v67, v62, v32
	v_dot4c_i32_i8_e32 v67, v63, v33
	v_and_b32_e32 v56, s21, v225
	v_lshrrev_b32_e32 v57, 4, v225
	v_and_b32_e32 v57, s21, v57
	v_and_b32_e32 v58, s21, v229
	v_lshrrev_b32_e32 v59, 4, v229
	v_and_b32_e32 v59, s21, v59
	v_and_b32_e32 v60, s21, v233
	v_lshrrev_b32_e32 v61, 4, v233
	v_and_b32_e32 v61, s21, v61
	v_and_b32_e32 v62, s21, v237
	v_lshrrev_b32_e32 v63, 4, v237
	v_and_b32_e32 v63, s21, v63
	v_dot4c_i32_i8_e32 v64, v56, v34
; __device__ __forceinline__ void phase_peer_u(const Params& p, int layer, int xs, int wid0, int wstride, char* smraw) {
;     ...
; #pragma unroll
;     for (int i = 0; i < 16; ++i) {
;       int a = 0;
; #pragma unroll
;       for (int m = 0; m < 4; ++m) {
;         const unsigned dw = q[i][m];
;         a = __builtin_amdgcn_sdot4((int)(dw & 0x0f0f0f0fu), xq[2 * m], a, false);
;         a = __builtin_amdgcn_sdot4((int)((dw >> 4) & 0x0f0f0f0fu), xq[2 * m + 1], a, false);
;       }
;       a -= corr;
;       a += __builtin_amdgcn_update_dpp(0, a, 0xB1, 0xF, 0xF, true);
;       a += __builtin_amdgcn_update_dpp(0, a, 0x4E, 0xF, 0xF, true);
;       a += __builtin_amdgcn_update_dpp(0, a, 0x141, 0xF, 0xF, true);
;       pr[i] = (float)a * sx;
;     }
;     if (j == 0) {
;       f32x4* dst = (f32x4*)((char*)p.actp + ((unsigned)t * 4096u + (unsigned)(sl * 512 + g * 64)));
; #pragma unroll
;       for (int q4 = 0; q4 < 4; ++q4) dst[q4] = f32x4{pr[q4 * 4], pr[q4 * 4 + 1], pr[q4 * 4 + 2], pr[q4 * 4 + 3]};
;     }
	v_dot4c_i32_i8_e32 v64, v57, v35
	v_dot4c_i32_i8_e32 v65, v58, v34
	v_dot4c_i32_i8_e32 v65, v59, v35
	v_dot4c_i32_i8_e32 v66, v60, v34
	v_dot4c_i32_i8_e32 v66, v61, v35
	v_dot4c_i32_i8_e32 v67, v62, v34
	v_dot4c_i32_i8_e32 v67, v63, v35
	v_and_b32_e32 v56, s21, v226
	v_lshrrev_b32_e32 v57, 4, v226
	v_and_b32_e32 v57, s21, v57
	v_and_b32_e32 v58, s21, v230
	v_lshrrev_b32_e32 v59, 4, v230
	v_and_b32_e32 v59, s21, v59
	v_and_b32_e32 v60, s21, v234
	v_lshrrev_b32_e32 v61, 4, v234
	v_and_b32_e32 v61, s21, v61
	v_and_b32_e32 v62, s21, v238
	v_lshrrev_b32_e32 v63, 4, v238
	v_and_b32_e32 v63, s21, v63
	v_dot4c_i32_i8_e32 v64, v56, v36
	v_dot4c_i32_i8_e32 v64, v57, v37
	v_dot4c_i32_i8_e32 v65, v58, v36
	v_dot4c_i32_i8_e32 v65, v59, v37
	v_dot4c_i32_i8_e32 v66, v60, v36
	v_dot4c_i32_i8_e32 v66, v61, v37
	v_dot4c_i32_i8_e32 v67, v62, v36
	v_dot4c_i32_i8_e32 v67, v63, v37
	v_and_b32_e32 v56, s21, v227
	v_lshrrev_b32_e32 v57, 4, v227
	v_and_b32_e32 v57, s21, v57
	v_and_b32_e32 v58, s21, v231
	v_lshrrev_b32_e32 v59, 4, v231
	v_and_b32_e32 v59, s21, v59
	v_and_b32_e32 v60, s21, v235
	v_lshrrev_b32_e32 v61, 4, v235
	v_and_b32_e32 v61, s21, v61
	v_and_b32_e32 v62, s21, v239
	v_lshrrev_b32_e32 v63, 4, v239
	v_and_b32_e32 v63, s21, v63
	v_dot4c_i32_i8_e32 v64, v56, v38
	v_dot4c_i32_i8_e32 v64, v57, v39
	v_dot4c_i32_i8_e32 v65, v58, v38
	v_dot4c_i32_i8_e32 v65, v59, v39
	v_dot4c_i32_i8_e32 v66, v60, v38
	v_dot4c_i32_i8_e32 v66, v61, v39
	v_dot4c_i32_i8_e32 v67, v62, v38
	v_dot4c_i32_i8_e32 v67, v63, v39
	v_add_u32_dpp v64, v64, v64 quad_perm:[1,0,3,2] row_mask:0xf bank_mask:0xf bound_ctrl:1
	v_add_u32_dpp v65, v65, v65 quad_perm:[1,0,3,2] row_mask:0xf bank_mask:0xf bound_ctrl:1
	v_add_u32_dpp v66, v66, v66 quad_perm:[1,0,3,2] row_mask:0xf bank_mask:0xf bound_ctrl:1
	v_add_u32_dpp v67, v67, v67 quad_perm:[1,0,3,2] row_mask:0xf bank_mask:0xf bound_ctrl:1
	v_add_u32_dpp v64, v64, v64 quad_perm:[2,3,0,1] row_mask:0xf bank_mask:0xf bound_ctrl:1
	v_add_u32_dpp v65, v65, v65 quad_perm:[2,3,0,1] row_mask:0xf bank_mask:0xf bound_ctrl:1
	v_add_u32_dpp v66, v66, v66 quad_perm:[2,3,0,1] row_mask:0xf bank_mask:0xf bound_ctrl:1
	v_add_u32_dpp v67, v67, v67 quad_perm:[2,3,0,1] row_mask:0xf bank_mask:0xf bound_ctrl:1
	v_add_u32_dpp v64, v64, v64 row_half_mirror row_mask:0xf bank_mask:0xf bound_ctrl:1
	v_add_u32_dpp v65, v65, v65 row_half_mirror row_mask:0xf bank_mask:0xf bound_ctrl:1
	v_add_u32_dpp v66, v66, v66 row_half_mirror row_mask:0xf bank_mask:0xf bound_ctrl:1
	v_add_u32_dpp v67, v67, v67 row_half_mirror row_mask:0xf bank_mask:0xf bound_ctrl:1
	v_cvt_f32_i32_e32 v80, v64
	v_cvt_f32_i32_e32 v81, v65
	v_cvt_f32_i32_e32 v82, v66
	v_cvt_f32_i32_e32 v83, v67
	v_pk_mul_f32 v[80:81], v[52:53], v[80:81] op_sel_hi:[0,1]
	v_pk_mul_f32 v[82:83], v[52:53], v[82:83] op_sel_hi:[0,1]
	s_lshl_b32 s70, s60, 1
	s_add_u32 s70, s70, s28
	s_lshl_b32 s70, s70, 12
	s_add_u32 s70, s70, s68
	s_mov_b64 s[74:75], exec
	s_and_b64 exec, exec, s[72:73]
	v_add_u32_e32 v9, s70, v5
	global_store_dwordx4 v9, v[68:71], s[64:65]
	global_store_dwordx4 v9, v[72:75], s[64:65] offset:16
	global_store_dwordx4 v9, v[76:79], s[64:65] offset:32
	global_store_dwordx4 v9, v[80:83], s[64:65] offset:48
	s_mov_b64 exec, s[74:75]
	s_mov_b32 s60, s62
	s_cmp_lt_u32 s60, s61
	s_cbranch_scc1 .Lmy_pu0_bodyA
.Lmy_pu0_done:
.LBB0_689:
	s_or_b64 exec, exec, s[8:9]
	s_waitcnt vmcnt(0)
	s_barrier
	s_mov_b64 s[6:7], exec
	v_readlane_b32 s8, v254, 16
	v_readlane_b32 s9, v254, 17
	s_and_b64 s[8:9], s[6:7], s[8:9]
	s_mov_b64 exec, s[8:9]
	s_cbranch_execz .LBB0_726
	s_mov_b64 s[10:11], exec
	s_waitcnt vmcnt(3)
	v_mbcnt_lo_u32_b32 v0, s10, 0
	v_mbcnt_hi_u32_b32 v0, s11, v0
	v_cmp_eq_u32_e32 vcc, 0, v0
	s_waitcnt vmcnt(0) expcnt(0) lgkmcnt(0)
	s_and_saveexec_b64 s[8:9], vcc
	s_cbranch_execz .LBB0_692
	s_bcnt1_i32_b64 s3, s[10:11]
	v_mov_b32_e32 v1, 0x1000
	v_mov_b32_e32 v2, s3
	global_atomic_add v1, v1, v2, s[78:79] offset:1024 sc0

; __device__ __forceinline__ int tid_opaque() { int t = threadIdx.x; asm volatile("" : "+v"(t)); return t; }
; __device__ __forceinline__ void phase_peer_u(const Params& p, int layer, int xs, int wid0, int wstride, char* smraw) {
;   const int tid = tid_opaque(), l = tid & 63, g = l >> 3, j = l & 7;
;   const int wid = wid0 + (tid >> 6);
;   char* xqs = smraw + (tid >> 6) * 256;
;   const int sl = xs >> 1, par = xs & 1;
;   constexpr int TH = T / 2;
;   const unsigned char* Uq = p.Uq + (size_t)(layer * 4 + sl) * NEXP * 128;
;   const unsigned joff = j * 16;
;   u32x4 ni[4];
;   auto load_idx = [&](int tt) {
;     const u32x4* ip = (const u32x4*)((const char*)p.sel_idx + ((unsigned)(2 * tt + par) * 512u + (unsigned)g * 64u));
; #pragma unroll
;     for (int q4 = 0; q4 < 4; ++q4) ni[q4] = ip[q4];
;   };
;   auto issue_rows = [&](int tt, u32x4 (&q)[16], u32x2& xv) {
; #pragma unroll
;     for (int i = 0; i < 16; ++i) q[i] = *(const u32x4*)(Uq + (ni[i >> 2][i & 3] * 128u + joff));
;     xv = *(const u32x2*)((const char*)p.hb + ((unsigned)(2 * tt + par) * 2048u + (unsigned)(sl * 512 + l * 8)));
;   };
;     ...
;   int tt = wid;
;   if (tt < TH) { load_idx(tt); issue_rows(tt, qA, xA); if (tt + wstride < TH) load_idx(tt + wstride); }
.LBB0_1265:
	s_or_b64 exec, exec, s[0:1]
	v_mov_b32_e32 v16, v189
	s_barrier
	s_lshl_b64 s[0:1], s[14:15], 21
	s_waitcnt vmcnt(0)
	v_ashrrev_i32_e32 v80, 6, v16
	v_add_u32_e32 v169, s92, v80
	s_add_u32 s15, s0, 0x800000
	s_movk_i32 s2, 0x4020
	s_addc_u32 s20, s1, 0
	v_cmp_gt_i32_e32 vcc, s2, v169
	s_and_saveexec_b64 s[0:1], vcc
	s_cbranch_execz .LBB0_1284
	v_and_b32_e32 v6, 63, v189
	v_lshrrev_b32_e32 v7, 6, v189
	v_lshlrev_b32_e32 v0, 3, v6
	v_and_b32_e32 v1, 7, v6
	v_cmp_eq_u32_e64 s[72:73], 0, v1
	v_lshlrev_b32_e32 v1, 4, v1
	v_lshrrev_b32_e32 v8, 3, v6
	v_readfirstlane_b32 s70, v7
	s_lshl_b32 s71, s28, 9
	v_lshl_add_u32 v2, v8, 6, s71
	v_lshlrev_b32_e32 v5, 6, v8
	v_lshlrev_b32_e32 v3, 8, v7
	v_lshl_add_u32 v4, v1, 1, v3
	v_lshl_add_u32 v3, v6, 2, v3
	s_add_u32 s60, s92, s70
	s_movk_i32 s61, 0x4020
	s_cmp_ge_u32 s60, s61
	s_cbranch_scc1 .Lmy_pu1_done
	s_lshl_b32 s70, s14, 21
	s_add_u32 s70, s70, 0x800000
	s_add_u32 s66, s88, s70
	s_addc_u32 s67, s89, 0
	v_readlane_b32 s64, v254, 4
	v_readlane_b32 s65, v254, 5
	s_lshl_b32 s68, s14, 9
	s_mov_b32 s69, 0x42fe0000
	s_mov_b32 s21, 0xf0f0f0f
	s_lshl_b32 s70, s60, 10
	v_add_u32_e32 v9, s70, v2
	global_load_dwordx4 v[10:13], v9, s[52:53]
	global_load_dwordx4 v[14:17], v9, s[52:53] offset:16
	global_load_dwordx4 v[18:21], v9, s[52:53] offset:32
	global_load_dwordx4 v[22:25], v9, s[52:53] offset:48
	s_waitcnt vmcnt(0)
	v_lshl_add_u32 v6, v10, 7, v1
	global_load_dwordx4 v[106:109], v6, s[66:67]
	v_lshl_add_u32 v7, v11, 7, v1
	global_load_dwordx4 v[110:113], v7, s[66:67]
	v_lshl_add_u32 v6, v12, 7, v1
	global_load_dwordx4 v[114:117], v6, s[66:67]
	v_lshl_add_u32 v7, v13, 7, v1
	global_load_dwordx4 v[118:121], v7, s[66:67]
	v_lshl_add_u32 v6, v14, 7, v1
	global_load_dwordx4 v[122:125], v6, s[66:67]
	v_lshl_add_u32 v7, v15, 7, v1
	global_load_dwordx4 v[126:129], v7, s[66:67]
	v_lshl_add_u32 v6, v16, 7, v1
	global_load_dwordx4 v[130:133], v6, s[66:67]
	v_lshl_add_u32 v7, v17, 7, v1
	global_load_dwordx4 v[134:137], v7, s[66:67]
	v_lshl_add_u32 v6, v18, 7, v1
	global_load_dwordx4 v[138:141], v6, s[66:67]
	v_lshl_add_u32 v7, v19, 7, v1
	global_load_dwordx4 v[142:145], v7, s[66:67]
	v_lshl_add_u32 v6, v20, 7, v1
	global_load_dwordx4 v[146:149], v6, s[66:67]
	v_lshl_add_u32 v7, v21, 7, v1
	global_load_dwordx4 v[150:153], v7, s[66:67]
	v_lshl_add_u32 v6, v22, 7, v1
	global_load_dwordx4 v[154:157], v6, s[66:67]
	v_lshl_add_u32 v7, v23, 7, v1
	global_load_dwordx4 v[158:161], v7, s[66:67]
	v_lshl_add_u32 v6, v24, 7, v1
	global_load_dwordx4 v[162:165], v6, s[66:67]
	v_lshl_add_u32 v7, v25, 7, v1
	global_load_dwordx4 v[166:169], v7, s[66:67]
	s_lshl_b32 s70, s60, 1
	s_add_u32 s70, s70, s28
	s_lshl_b32 s70, s70, 11
	s_add_u32 s70, s70, s68
	v_add_u32_e32 v8, s70, v0
	global_load_dwordx2 v[26:27], v8, s[76:77]
	s_add_u32 s62, s60, s33
	s_cmp_ge_u32 s62, s61
	s_cbranch_scc1 .Lmy_pu1_pro1
	s_lshl_b32 s70, s62, 10
	v_add_u32_e32 v9, s70, v2
	global_load_dwordx4 v[10:13], v9, s[52:53]
	global_load_dwordx4 v[14:17], v9, s[52:53] offset:16
	global_load_dwordx4 v[18:21], v9, s[52:53] offset:32
	global_load_dwordx4 v[22:25], v9, s[52:53] offset:48

; __device__ __forceinline__ unsigned xb_add(unsigned* p, unsigned v) { return __hip_atomic_fetch_add(p, v, __ATOMIC_RELAXED, __HIP_MEMORY_SCOPE_AGENT); }
; __device__ __forceinline__ void xcd_barrier(const XcdBarrier& b) {
;   asm volatile("s_waitcnt vmcnt(0)" ::: "memory");
;   __syncthreads();
;   if (threadIdx.x == 0) {
;     unsigned* bar = b.bar;
;     __builtin_amdgcn_s_waitcnt(0);
;     const unsigned old = xb_add(&bar[XB_XSUB(b.x)], 1u);
;     const unsigned gen = old / b.nloc;
;     if (old + 1u == (gen + 1u) * b.nloc) {
.Lmy_pu1_done:
.LBB0_1284:
	s_or_b64 exec, exec, s[0:1]
	s_waitcnt vmcnt(0)
	s_barrier
	s_mov_b64 s[0:1], exec
	v_readlane_b32 s2, v254, 16
	v_readlane_b32 s3, v254, 17
	s_and_b64 s[2:3], s[0:1], s[2:3]
	s_mov_b64 exec, s[2:3]
	s_cbranch_execz .LBB0_1321
	s_mov_b64 s[4:5], exec
	s_waitcnt vmcnt(3)
	v_mbcnt_lo_u32_b32 v0, s4, 0
	v_mbcnt_hi_u32_b32 v0, s5, v0
	v_cmp_eq_u32_e32 vcc, 0, v0
	s_waitcnt vmcnt(0) expcnt(0) lgkmcnt(0)
	s_and_saveexec_b64 s[2:3], vcc
	s_cbranch_execz .LBB0_1287
	s_bcnt1_i32_b64 s4, s[4:5]
	v_mov_b32_e32 v1, 0x1000
	v_mov_b32_e32 v2, s4
	global_atomic_add v1, v1, v2, s[78:79] offset:1024 sc0
